# v80 + retention: waves 5 and 6 exchange roles so the SIMD wave pairs carry 88/80/88/80 instead of 88/72/96/80 MFMAs per half step
# baseline (speedup 1.0000x reference)
.LBB0_884:
	s_cmp_lt_i32 s90, 11
	s_cselect_b64 s[0:1], -1, 0
	s_and_b64 s[2:3], s[0:1], s[2:3]
	s_andn2_b64 vcc, exec, s[2:3]
	s_cbranch_vccnz .LBB0_1005
	v_lshrrev_b32_e32 v0, 6, v248
	v_add_u32_e32 v0, -5, v0
	v_cmp_gt_u32_e32 vcc, 2, v0
	v_mov_b32_e32 v0, 0xc0
	s_nop 0
	v_cndmask_b32_e32 v0, 0, v0, vcc
	v_xor_b32_e32 v0, v0, v248
	s_cmpk_gt_i32 s81, 0x1ff
	s_cbranch_scc1 .LBB0_1005
	s_add_u32 s60, s88, 0xd000000
	s_addc_u32 s61, s89, 0
	s_add_u32 s62, s88, 0x16000000
	s_addc_u32 s63, s89, 0
	s_add_u32 s64, s88, 0x1f000000
	s_addc_u32 s65, s89, 0
	s_add_u32 s66, s88, 0x3c00000
	s_addc_u32 s67, s89, 0
	s_waitcnt lgkmcnt(0)
	v_and_b32_e32 v2, 15, v0
	v_ashrrev_i32_e32 v11, 6, v0
	s_cmpk_eq_i32 s84, 0x100
	v_and_b32_e32 v193, 31, v0
	v_bfe_u32 v201, v0, 5, 1
	v_ashrrev_i32_e32 v202, 4, v0
	v_ashrrev_i32_e32 v1, 7, v0
	v_lshlrev_b32_e32 v3, 2, v0
	v_and_b32_e32 v4, 16, v0
	v_lshrrev_b32_e32 v7, 2, v0
	v_and_b32_e32 v12, 1, v11
	v_ashrrev_i32_e32 v13, 8, v0
	v_and_b32_e32 v11, 3, v11
	s_cselect_b64 s[24:25], -1, 0
	v_lshlrev_b32_e32 v0, 4, v2
	s_add_i32 s8, 0, 0x11000
	v_lshlrev_b32_e32 v6, 3, v201
	s_movk_i32 s14, 0x88
	v_add_u32_e32 v192, 0, v0
	v_add_u32_e32 v204, s8, v0
	v_lshl_or_b32 v0, v11, 5, v193
	v_mad_u32_u24 v10, v193, s14, v6
	v_mul_u32_u24_e32 v0, 0x110, v0
	s_add_i32 s2, 0, 0x19800
	v_lshlrev_b32_e32 v14, 7, v13
	v_add3_u32 v15, s2, v0, v14
	v_lshl_add_u32 v0, v10, 1, 0
	s_movk_i32 s6, 0x2200
	v_and_b32_e32 v3, 12, v3
	v_and_or_b32 v7, v7, 3, v6
	v_mad_u64_u32 v[194:195], s[6:7], v1, s6, v[0:1]
	v_or_b32_e32 v5, v3, v4
	v_mul_u32_u24_e32 v8, 0x88, v7
	s_movk_i32 s6, 0x4400
	v_lshlrev_b32_e32 v16, 1, v12
	v_mad_i32_i24 v195, v13, s6, v0
	v_add_lshl_u32 v0, v8, v5, 1
	v_lshlrev_b32_e32 v5, 6, v11
	v_add3_u32 v8, s8, v0, v5
	v_or_b32_e32 v0, 1, v16
	v_mul_u32_u24_e32 v9, 0x88, v193
	v_mul_u32_u24_e32 v10, 0x4400, v12
	v_cmp_eq_u32_e64 s[12:13], v0, v1
	v_lshlrev_b32_e32 v210, 5, v0
	v_lshlrev_b32_e32 v0, 4, v201
	v_or_b32_e32 v10, v10, v0
	v_lshlrev_b32_e32 v9, 1, v9
	v_mad_u32_u24 v4, v7, s14, v4
	v_mul_u32_u24_e32 v17, 0x2200, v11
	v_mul_i32_i24_e32 v18, 0x4400, v13
	v_lshl_or_b32 v206, v13, 2, 2
	s_movk_i32 s15, 0x1100
	v_add3_u32 v10, v10, v9, 0
	v_add_lshl_u32 v3, v4, v3, 1
	v_lshlrev_b32_e32 v203, 3, v2
	v_cmp_le_i32_e64 s[2:3], v16, v1
	v_cmp_lt_i32_e64 s[4:5], v16, v1
	v_lshlrev_b32_e32 v205, 5, v1
	v_cmp_eq_u32_e64 s[8:9], 0, v2
	v_cmp_eq_u32_e64 s[10:11], v16, v1
	v_mul_lo_u32 v1, v206, s15
	v_lshlrev_b32_e32 v2, 5, v206
	v_or_b32_e32 v11, 0x60, v14
	v_add_u32_e32 v211, 0x8800, v10
	v_or_b32_e32 v10, v17, v0
	v_add_u32_e32 v214, v5, v3
	v_or_b32_e32 v0, v18, v0
	s_mov_b32 s29, 0
	s_movk_i32 s68, 0x110
	v_cmp_lt_i32_e64 s[6:7], -1, v13
	v_lshlrev_b32_e32 v207, 6, v13
	v_add_u32_e32 v208, 0, v5
	v_lshlrev_b32_e32 v209, 6, v12
	v_add3_u32 v212, v10, v9, 0
	v_add3_u32 v213, v14, v3, 0
	v_add_u32_e32 v215, 0, v214
	v_add_u32_e32 v216, v0, v9
	v_mov_b32_e32 v0, 0
	s_mov_b32 s69, 0x3f2aaaab
	v_mov_b32_e32 v217, 0x3ecc95a3
	s_mov_b32 s70, 0x3f317218
	s_mov_b32 s71, 0x7f800000
	s_mov_b32 s72, 0x33800000
	s_mov_b32 s73, 0xc2fc0000
	v_add_u32_e32 v218, v8, v1
	v_add_u32_e32 v219, v195, v2
	v_add_u32_e32 v220, v195, v11
	v_mov_b32_e32 v221, 0x7f800000
	v_mov_b32_e32 v222, 0x7fc00000
	v_mov_b32_e32 v223, 0xff800000
	v_mov_b32_e32 v224, 0x42800000
	v_add_u32_e32 v225, v15, v6
	v_mbcnt_lo_u32_b32 v226, -1, 0
	s_mov_b32 s74, s81
	v_lshrrev_b32_e32 v14, 6, v248
	v_add_u32_e32 v14, -5, v14
	v_cmp_gt_u32_e64 s[96:97], 2, v14
	v_mov_b32_e32 v14, 0xc0
	s_nop 0
	v_cndmask_b32_e64 v14, 0, v14, s[96:97]
	v_xor_b32_e32 v14, v14, v248
	v_lshrrev_b32_e32 v2, 4, v14
	v_and_b32_e32 v3, 15, v14
	v_and_b32_e32 v4, 3, v2
	v_bfe_u32 v5, v2, 2, 2
	v_lshl_or_b32 v4, v4, 2, v5
	v_xor_b32_e32 v3, v3, v4
	v_lshlrev_b32_e32 v3, 4, v3
	v_lshl_or_b32 v249, v2, 8, v3
	v_and_b32_e32 v2, 31, v14
	v_bfe_u32 v3, v14, 5, 1
	v_and_b32_e32 v4, 3, v2
	v_bfe_u32 v5, v2, 2, 2
	v_lshl_or_b32 v4, v4, 2, v5
	v_xor_b32_e32 v4, v4, v3
	v_lshlrev_b32_e32 v4, 4, v4
	v_bfe_u32 v5, v14, 6, 1
	v_lshl_or_b32 v5, v5, 6, v2
	v_lshl_or_b32 v4, v5, 8, v4
	v_add_u32_e32 v250, 0x8800, v4
	v_bfe_u32 v2, v14, 5, 1
	v_bfe_u32 v3, v14, 2, 2
	v_bfe_u32 v4, v14, 4, 1
	v_and_b32_e32 v5, 3, v14
	v_lshrrev_b32_e32 v6, 1, v5
	v_lshl_or_b32 v6, v4, 1, v6
	v_and_b32_e32 v5, 1, v5
	v_lshlrev_b32_e32 v5, 3, v5
	v_lshlrev_b32_e32 v7, 1, v2
	v_xor_b32_e32 v8, v6, v7
	v_or_b32_e32 v7, 1, v7
	v_xor_b32_e32 v9, v6, v7
	v_lshl_or_b32 v8, v8, 4, v5
	v_lshl_or_b32 v9, v9, 4, v5
	v_lshl_or_b32 v2, v2, 3, v3
	v_lshl_add_u32 v8, v2, 8, v8
	v_lshl_add_u32 v9, v2, 8, v9
	v_add_u32_e32 v9, 0x400, v9
	v_lshrrev_b32_e32 v4, 8, v14
	v_lshlrev_b32_e32 v4, 1, v4
	v_xor_b32_e32 v6, v4, v3
	v_or_b32_e32 v4, 1, v4
	v_xor_b32_e32 v7, v4, v3
	v_bfe_u32 v4, v14, 6, 2
	v_xor_b32_e32 v4, v4, v3
	v_lshlrev_b32_e32 v6, 6, v6
	v_lshlrev_b32_e32 v7, 6, v7
	v_lshlrev_b32_e32 v4, 6, v4
	v_add_u32_e32 v10, 0x8800, v8
	v_add_u32_e32 v11, 0x8800, v9
	v_add_u32_e32 v12, 0x11000, v8
	v_add_u32_e32 v13, 0x11000, v9
	v_add_u32_e32 v251, v10, v6
	v_add_u32_e32 v252, v11, v6
	v_add_u32_e32 v253, v10, v7
	v_add_u32_e32 v200, v11, v7
	v_add_u32_e32 v235, v12, v4
	v_add_u32_e32 v255, v13, v4
	s_branch .LBB0_888
